# weight conversion (w_in both layers, w_up layer 1) rewritten: two tiles of loads in flight per workgroup through two register sets
# baseline (speedup 1.0000x reference)
; #define LAS __attribute__((address_space(3)))
; __device__ __forceinline__ int opaque_tid(int wv) { asm volatile("" : "+s"(wv)); unsigned z = 0u; asm volatile("" : "+v"(z)); const int l = __builtin_amdgcn_mbcnt_hi(~0u, __builtin_amdgcn_mbcnt_lo(~0u, z)); return (wv << 6) | l; }
; __device__ __forceinline__ void convert_weight(int wv, const float* __restrict__ src, int ldsrc, int Ksrc, bf16_t* dst, int ldd, int koff, int ntn, const float* kscale, int mode, LAS float* tile, int pidx, int pcnt) {
;     const int tid = opaque_tid(wv); const int ntk = Ksrc / 128; const int total = ntn * ntk; const int G = pcnt;
;     const int kk0 = tid >> 4, n4 = (tid & 15) * 4;
;     f32x4 v[4]; float ks[4];
;     auto prefetch = [&](int t) {
;         const int tn = t % ntn, tk = t / ntn; const int n0 = tn * 64, k0 = tk * 128;
;         int scol = n0, nvalid = 64;
;         if (mode == 1) { if (n0 < 5632) scol = n0; else if (n0 < 13312) scol = n0 + 8; else if (n0 == 13312) { scol = 5632; nvalid = 8; } else { scol = 0; nvalid = 0; } }
; #pragma unroll
;         for (int i = 0; i < 4; ++i) { const int kk = kk0 + i * 32; v[i] = (f32x4){0.f, 0.f, 0.f, 0.f};
;             if (n4 < nvalid) v[i] = *(const f32x4*)(src + (size_t)(k0 + kk) * ldsrc + scol + n4);
;             ks[i] = kscale ? kscale[k0 + kk] : 1.0f; }
;     };
;     int t = pidx; int buf = 0;
;     if (t < total) prefetch(t);
.LBB0_3:
	s_or_b64 exec, exec, s[4:5]
	s_mov_b64 s[4:5], s[0:1]
	s_mov_b32 s26, s81
	s_waitcnt lgkmcnt(0)
	s_barrier
	s_mov_b32 s15, s95
	s_cmpk_gt_i32 s26, 0xd3f
	s_cbranch_scc1 .LBB0_61
	v_mbcnt_lo_u32_b32 v10, -1, 0
	v_mbcnt_hi_u32_b32 v10, -1, v10
	v_lshl_or_b32 v10, s95, 6, v10
	v_lshrrev_b32_e32 v11, 4, v10
	v_and_b32_e32 v9, 15, v10
	v_lshlrev_b32_e32 v9, 2, v9
	v_mul_u32_u24_e32 v4, 0x3408, v11
	v_add_u32_e32 v4, v4, v9
	v_lshlrev_b32_e32 v4, 2, v4
	v_lshlrev_b32_e32 v5, 2, v11
	v_mul_u32_u24_e32 v6, 65, v11
	v_add_u32_e32 v6, v6, v9
	v_lshlrev_b32_e32 v6, 2, v6
	v_lshrrev_b32_e32 v7, 3, v10
	v_and_b32_e32 v8, 7, v10
	v_lshlrev_b32_e32 v8, 4, v8
	v_mul_u32_u24_e32 v11, 65, v8
	v_add_u32_e32 v11, v11, v7
	v_lshlrev_b32_e32 v8, 1, v8
	v_lshl_add_u32 v8, v7, 12, v8
	v_lshlrev_b32_e32 v7, 2, v11
	s_load_dwordx2 s[4:5], s[0:1], 0x18
	s_load_dwordx2 s[6:7], s[0:1], 0x10
	s_load_dwordx2 s[8:9], s[0:1], 0xa0
	s_waitcnt lgkmcnt(0)
	s_add_u32 s8, s8, 0x23100000
	s_addc_u32 s9, s9, 0
	s_mov_b32 s10, s26
	s_mul_hi_u32 s15, s10, 0x13521d0
	s_mul_i32 s14, s15, 212
	s_sub_u32 s14, s10, s14
	s_lshl_b32 s18, s14, 6
	s_mov_b32 s28, 0
	s_cmp_lt_u32 s14, 88
	s_cbranch_scc1 .Lcv0_cp0
	s_add_u32 s18, s18, 8
	s_cmp_lt_u32 s14, 208
	s_cbranch_scc1 .Lcv0_cp0
	s_movk_i32 s18, 0x1600
	s_mov_b32 s28, 1
	s_cmp_eq_u32 s14, 208
	s_cbranch_scc1 .Lcv0_cp0
	s_mov_b32 s18, 0
	s_mov_b32 s28, 2
.Lcv0_cp0:
	s_mul_i32 s19, s15, 0x1a0400
	s_add_u32 s19, s19, s18
	s_lshl_b32 s19, s19, 2
	s_add_u32 s20, s4, s19
	s_addc_u32 s21, s5, 0
	s_lshl_b32 s19, s15, 9
	s_add_u32 s22, s6, s19
	s_addc_u32 s23, s7, 0
	global_load_dwordx4 v[12:15], v4, s[20:21]
	global_load_dword v28, v5, s[22:23]
	s_add_u32 s20, s20, 0x1a0400
	s_addc_u32 s21, s21, 0
	global_load_dwordx4 v[16:19], v4, s[20:21]
	global_load_dword v29, v5, s[22:23] offset:128
	s_add_u32 s20, s20, 0x1a0400
	s_addc_u32 s21, s21, 0
	global_load_dwordx4 v[20:23], v4, s[20:21]
	global_load_dword v30, v5, s[22:23] offset:256
	s_add_u32 s20, s20, 0x1a0400
	s_addc_u32 s21, s21, 0
	global_load_dwordx4 v[24:27], v4, s[20:21]
	global_load_dword v31, v5, s[22:23] offset:384
	s_add_u32 s11, s10, 256
	s_cmp_lt_u32 s11, 3392
	s_cbranch_scc0 .Lcv0_p1n
	s_mul_hi_u32 s15, s11, 0x13521d0
	s_mul_i32 s14, s15, 212
	s_sub_u32 s14, s11, s14
	s_lshl_b32 s18, s14, 6
	s_mov_b32 s29, 0
	s_cmp_lt_u32 s14, 88
	s_cbranch_scc1 .Lcv0_cp1
	s_add_u32 s18, s18, 8
	s_cmp_lt_u32 s14, 208
	s_cbranch_scc1 .Lcv0_cp1
	s_movk_i32 s18, 0x1600
	s_mov_b32 s29, 1
	s_cmp_eq_u32 s14, 208
	s_cbranch_scc1 .Lcv0_cp1
	s_mov_b32 s18, 0
	s_mov_b32 s29, 2
.Lcv0_cp1:
	s_mul_i32 s19, s15, 0x1a0400
	s_add_u32 s19, s19, s18
	s_lshl_b32 s19, s19, 2
	s_add_u32 s20, s4, s19
	s_addc_u32 s21, s5, 0
	s_lshl_b32 s19, s15, 9
	s_add_u32 s22, s6, s19
	s_addc_u32 s23, s7, 0
	global_load_dwordx4 v[32:35], v4, s[20:21]
	global_load_dword v48, v5, s[22:23]
	s_add_u32 s20, s20, 0x1a0400
	s_addc_u32 s21, s21, 0
	global_load_dwordx4 v[36:39], v4, s[20:21]
	global_load_dword v49, v5, s[22:23] offset:128
	s_add_u32 s20, s20, 0x1a0400
	s_addc_u32 s21, s21, 0
	global_load_dwordx4 v[40:43], v4, s[20:21]
	global_load_dword v50, v5, s[22:23] offset:256
	s_add_u32 s20, s20, 0x1a0400
	s_addc_u32 s21, s21, 0
	global_load_dwordx4 v[44:47], v4, s[20:21]
	global_load_dword v51, v5, s[22:23] offset:384
	s_waitcnt vmcnt(8)
	s_branch .Lcv0_loop

; #define LAS __attribute__((address_space(3)))
; __device__ __forceinline__ void lds_barrier() { asm volatile("s_waitcnt lgkmcnt(0)" ::: "memory"); __builtin_amdgcn_s_barrier(); asm volatile("" ::: "memory"); }
; __device__ __forceinline__ unsigned pack2(float lo, float hi) { unsigned r; asm("v_cvt_pk_bf16_f32 %0, %1, %2" : "=v"(r) : "v"(lo), "v"(hi)); return r; }
; __device__ __forceinline__ void convert_weight(int wv, const float* __restrict__ src, int ldsrc, int Ksrc, bf16_t* dst, int ldd, int koff, int ntn, const float* kscale, int mode, LAS float* tile, int pidx, int pcnt) {
;     ...
;     for (; t < total; t += G) {
;         LAS float* tl = tile + buf * (128 * 65);
; #pragma unroll
;         for (int i = 0; i < 4; ++i) { const int kk = kk0 + i * 32;
;             tl[kk * 65 + n4 + 0] = v[i][0] * ks[i]; tl[kk * 65 + n4 + 1] = v[i][1] * ks[i]; tl[kk * 65 + n4 + 2] = v[i][2] * ks[i]; tl[kk * 65 + n4 + 3] = v[i][3] * ks[i]; }
;         lds_barrier();
;         const int tn = t % ntn, tk = t / ntn; const int n0 = tn * 64, k0 = tk * 128;
;         if (t + G < total) prefetch(t + G);
;         { const int n = tid >> 3, k16 = (tid & 7) * 16; u32x4 w0, w1;
;           w0.x = pack2(tl[(k16 + 0) * 65 + n], tl[(k16 + 1) * 65 + n]); w0.y = pack2(tl[(k16 + 2) * 65 + n], tl[(k16 + 3) * 65 + n]);
;           w0.z = pack2(tl[(k16 + 4) * 65 + n], tl[(k16 + 5) * 65 + n]); w0.w = pack2(tl[(k16 + 6) * 65 + n], tl[(k16 + 7) * 65 + n]);
;           w1.x = pack2(tl[(k16 + 8) * 65 + n], tl[(k16 + 9) * 65 + n]); w1.y = pack2(tl[(k16 + 10) * 65 + n], tl[(k16 + 11) * 65 + n]);
;           w1.z = pack2(tl[(k16 + 12) * 65 + n], tl[(k16 + 13) * 65 + n]); w1.w = pack2(tl[(k16 + 14) * 65 + n], tl[(k16 + 15) * 65 + n]);
;           bf16_t* dp = dst + (size_t)(n0 + n) * ldd + koff + k0 + k16; *(u32x4*)dp = w0; *(u32x4*)(dp + 8) = w1; }
;         buf ^= 1;
.Lcv0_loop:
	s_cmp_eq_u32 s28, 0
	s_cbranch_scc1 .Lcv0_ma
	s_cmp_eq_u32 s28, 1
	s_cselect_b32 s19, 8, 0
	v_cmp_gt_u32_e32 vcc, s19, v9
	s_nop 1
	v_cndmask_b32_e32 v12, 0, v12, vcc
	v_cndmask_b32_e32 v13, 0, v13, vcc
	v_cndmask_b32_e32 v14, 0, v14, vcc
	v_cndmask_b32_e32 v15, 0, v15, vcc
	v_cndmask_b32_e32 v16, 0, v16, vcc
	v_cndmask_b32_e32 v17, 0, v17, vcc
	v_cndmask_b32_e32 v18, 0, v18, vcc
	v_cndmask_b32_e32 v19, 0, v19, vcc
	v_cndmask_b32_e32 v20, 0, v20, vcc
	v_cndmask_b32_e32 v21, 0, v21, vcc
	v_cndmask_b32_e32 v22, 0, v22, vcc
	v_cndmask_b32_e32 v23, 0, v23, vcc
	v_cndmask_b32_e32 v24, 0, v24, vcc
	v_cndmask_b32_e32 v25, 0, v25, vcc
	v_cndmask_b32_e32 v26, 0, v26, vcc
	v_cndmask_b32_e32 v27, 0, v27, vcc
.Lcv0_ma:
	v_mul_f32_e32 v12, v12, v28
	v_mul_f32_e32 v13, v13, v28
	v_mul_f32_e32 v14, v14, v28
	v_mul_f32_e32 v15, v15, v28
	v_mul_f32_e32 v16, v16, v29
	v_mul_f32_e32 v17, v17, v29
	v_mul_f32_e32 v18, v18, v29
	v_mul_f32_e32 v19, v19, v29
	v_mul_f32_e32 v20, v20, v30
	v_mul_f32_e32 v21, v21, v30
	v_mul_f32_e32 v22, v22, v30
	v_mul_f32_e32 v23, v23, v30
	v_mul_f32_e32 v24, v24, v31
	v_mul_f32_e32 v25, v25, v31
	v_mul_f32_e32 v26, v26, v31
	v_mul_f32_e32 v27, v27, v31
	ds_write_b32 v6, v12 offset:0
	ds_write_b32 v6, v13 offset:4
	ds_write_b32 v6, v14 offset:8
	ds_write_b32 v6, v15 offset:12
	ds_write_b32 v6, v16 offset:8320
	ds_write_b32 v6, v17 offset:8324
	ds_write_b32 v6, v18 offset:8328
	ds_write_b32 v6, v19 offset:8332
	ds_write_b32 v6, v20 offset:16640
	ds_write_b32 v6, v21 offset:16644
	ds_write_b32 v6, v22 offset:16648
	ds_write_b32 v6, v23 offset:16652
	ds_write_b32 v6, v24 offset:24960
	ds_write_b32 v6, v25 offset:24964
	ds_write_b32 v6, v26 offset:24968
	ds_write_b32 v6, v27 offset:24972
	s_waitcnt lgkmcnt(0)
	s_barrier
	s_add_u32 s11, s10, 512
	s_mov_b32 s27, 0
	s_cmp_lt_u32 s11, 3392
	s_cbranch_scc0 .Lcv0_na
	s_mov_b32 s27, 1
	s_mul_hi_u32 s15, s11, 0x13521d0
	s_mul_i32 s14, s15, 212
	s_sub_u32 s14, s11, s14
	s_lshl_b32 s18, s14, 6
	s_mov_b32 s28, 0
	s_cmp_lt_u32 s14, 88
	s_cbranch_scc1 .Lcv0_ca
	s_add_u32 s18, s18, 8
	s_cmp_lt_u32 s14, 208
	s_cbranch_scc1 .Lcv0_ca
	s_movk_i32 s18, 0x1600
	s_mov_b32 s28, 1
	s_cmp_eq_u32 s14, 208
	s_cbranch_scc1 .Lcv0_ca
	s_mov_b32 s18, 0
	s_mov_b32 s28, 2
.Lcv0_ca:
	s_mul_i32 s19, s15, 0x1a0400
	s_add_u32 s19, s19, s18
	s_lshl_b32 s19, s19, 2
	s_add_u32 s20, s4, s19
	s_addc_u32 s21, s5, 0
	s_lshl_b32 s19, s15, 9
	s_add_u32 s22, s6, s19
	s_addc_u32 s23, s7, 0
	global_load_dwordx4 v[12:15], v4, s[20:21]
	global_load_dword v28, v5, s[22:23]
	s_add_u32 s20, s20, 0x1a0400
	s_addc_u32 s21, s21, 0
	global_load_dwordx4 v[16:19], v4, s[20:21]
	global_load_dword v29, v5, s[22:23] offset:128
	s_add_u32 s20, s20, 0x1a0400
	s_addc_u32 s21, s21, 0
	global_load_dwordx4 v[20:23], v4, s[20:21]
	global_load_dword v30, v5, s[22:23] offset:256
	s_add_u32 s20, s20, 0x1a0400
	s_addc_u32 s21, s21, 0
	global_load_dwordx4 v[24:27], v4, s[20:21]
	global_load_dword v31, v5, s[22:23] offset:384
.Lcv0_na:
	ds_read_b32 v52, v7 offset:0
	ds_read_b32 v53, v7 offset:260
	ds_read_b32 v54, v7 offset:520
	ds_read_b32 v55, v7 offset:780
	ds_read_b32 v56, v7 offset:1040
	ds_read_b32 v57, v7 offset:1300
	ds_read_b32 v58, v7 offset:1560
	ds_read_b32 v59, v7 offset:1820
	ds_read_b32 v60, v7 offset:2080
	ds_read_b32 v61, v7 offset:2340
	ds_read_b32 v62, v7 offset:2600
	ds_read_b32 v63, v7 offset:2860
	ds_read_b32 v64, v7 offset:3120
	ds_read_b32 v65, v7 offset:3380
	ds_read_b32 v66, v7 offset:3640
	ds_read_b32 v67, v7 offset:3900
	s_mul_hi_u32 s15, s10, 0x13521d0
	s_mul_i32 s14, s15, 212
	s_sub_u32 s14, s10, s14
	s_lshl_b32 s14, s14, 18
	s_lshl_b32 s15, s15, 8
	s_add_u32 s14, s14, s15
	s_add_u32 s24, s8, s14
	s_addc_u32 s25, s9, 0
	s_waitcnt lgkmcnt(14)
	v_cvt_pk_bf16_f32 v68, v52, v53
	s_waitcnt lgkmcnt(12)
	v_cvt_pk_bf16_f32 v69, v54, v55
	s_waitcnt lgkmcnt(10)
	v_cvt_pk_bf16_f32 v70, v56, v57
	s_waitcnt lgkmcnt(8)
	v_cvt_pk_bf16_f32 v71, v58, v59
	s_waitcnt lgkmcnt(6)
	v_cvt_pk_bf16_f32 v72, v60, v61
	s_waitcnt lgkmcnt(4)
	v_cvt_pk_bf16_f32 v73, v62, v63
	s_waitcnt lgkmcnt(2)
	v_cvt_pk_bf16_f32 v74, v64, v65
	s_waitcnt lgkmcnt(0)
	v_cvt_pk_bf16_f32 v75, v66, v67
	global_store_dwordx4 v8, v[68:71], s[24:25]
	global_store_dwordx4 v8, v[72:75], s[24:25] offset:16
	s_add_u32 s10, s10, 256
	s_cmp_lt_u32 s10, 3392
	s_cbranch_scc0 .Lcv0_end
	s_cmp_eq_u32 s27, 0
	s_cbranch_scc1 .Lcv0_wa
	s_waitcnt vmcnt(10)
	s_branch .Lcv0_xa
.Lcv0_wa:
	s_waitcnt vmcnt(2)
; #define LAS __attribute__((address_space(3)))
; __device__ __forceinline__ void lds_barrier() { asm volatile("s_waitcnt lgkmcnt(0)" ::: "memory"); __builtin_amdgcn_s_barrier(); asm volatile("" ::: "memory"); }
; __device__ __forceinline__ unsigned pack2(float lo, float hi) { unsigned r; asm("v_cvt_pk_bf16_f32 %0, %1, %2" : "=v"(r) : "v"(lo), "v"(hi)); return r; }
; __device__ __forceinline__ void convert_weight(int wv, const float* __restrict__ src, int ldsrc, int Ksrc, bf16_t* dst, int ldd, int koff, int ntn, const float* kscale, int mode, LAS float* tile, int pidx, int pcnt) {
;     ...
;     for (; t < total; t += G) {
;         LAS float* tl = tile + buf * (128 * 65);
; #pragma unroll
;         for (int i = 0; i < 4; ++i) { const int kk = kk0 + i * 32;
;             tl[kk * 65 + n4 + 0] = v[i][0] * ks[i]; tl[kk * 65 + n4 + 1] = v[i][1] * ks[i]; tl[kk * 65 + n4 + 2] = v[i][2] * ks[i]; tl[kk * 65 + n4 + 3] = v[i][3] * ks[i]; }
;         lds_barrier();
;         const int tn = t % ntn, tk = t / ntn; const int n0 = tn * 64, k0 = tk * 128;
;         if (t + G < total) prefetch(t + G);
;         { const int n = tid >> 3, k16 = (tid & 7) * 16; u32x4 w0, w1;
;           w0.x = pack2(tl[(k16 + 0) * 65 + n], tl[(k16 + 1) * 65 + n]); w0.y = pack2(tl[(k16 + 2) * 65 + n], tl[(k16 + 3) * 65 + n]);
;           w0.z = pack2(tl[(k16 + 4) * 65 + n], tl[(k16 + 5) * 65 + n]); w0.w = pack2(tl[(k16 + 6) * 65 + n], tl[(k16 + 7) * 65 + n]);
;           w1.x = pack2(tl[(k16 + 8) * 65 + n], tl[(k16 + 9) * 65 + n]); w1.y = pack2(tl[(k16 + 10) * 65 + n], tl[(k16 + 11) * 65 + n]);
;           w1.z = pack2(tl[(k16 + 12) * 65 + n], tl[(k16 + 13) * 65 + n]); w1.w = pack2(tl[(k16 + 14) * 65 + n], tl[(k16 + 15) * 65 + n]);
;           bf16_t* dp = dst + (size_t)(n0 + n) * ldd + koff + k0 + k16; *(u32x4*)dp = w0; *(u32x4*)(dp + 8) = w1; }
;         buf ^= 1;
;     }
.Lcv0_xa:
	s_cmp_eq_u32 s29, 0
	s_cbranch_scc1 .Lcv0_mb
	s_cmp_eq_u32 s29, 1
	s_cselect_b32 s19, 8, 0
	v_cmp_gt_u32_e32 vcc, s19, v9
	s_nop 1
	v_cndmask_b32_e32 v32, 0, v32, vcc
	v_cndmask_b32_e32 v33, 0, v33, vcc
	v_cndmask_b32_e32 v34, 0, v34, vcc
	v_cndmask_b32_e32 v35, 0, v35, vcc
	v_cndmask_b32_e32 v36, 0, v36, vcc
	v_cndmask_b32_e32 v37, 0, v37, vcc
	v_cndmask_b32_e32 v38, 0, v38, vcc
	v_cndmask_b32_e32 v39, 0, v39, vcc
	v_cndmask_b32_e32 v40, 0, v40, vcc
	v_cndmask_b32_e32 v41, 0, v41, vcc
	v_cndmask_b32_e32 v42, 0, v42, vcc
	v_cndmask_b32_e32 v43, 0, v43, vcc
	v_cndmask_b32_e32 v44, 0, v44, vcc
	v_cndmask_b32_e32 v45, 0, v45, vcc
	v_cndmask_b32_e32 v46, 0, v46, vcc
	v_cndmask_b32_e32 v47, 0, v47, vcc
.Lcv0_mb:
	v_mul_f32_e32 v32, v32, v48
	v_mul_f32_e32 v33, v33, v48
	v_mul_f32_e32 v34, v34, v48
	v_mul_f32_e32 v35, v35, v48
	v_mul_f32_e32 v36, v36, v49
	v_mul_f32_e32 v37, v37, v49
	v_mul_f32_e32 v38, v38, v49
	v_mul_f32_e32 v39, v39, v49
	v_mul_f32_e32 v40, v40, v50
	v_mul_f32_e32 v41, v41, v50
	v_mul_f32_e32 v42, v42, v50
	v_mul_f32_e32 v43, v43, v50
	v_mul_f32_e32 v44, v44, v51
	v_mul_f32_e32 v45, v45, v51
	v_mul_f32_e32 v46, v46, v51
	v_mul_f32_e32 v47, v47, v51
	ds_write_b32 v6, v32 offset:33280
	ds_write_b32 v6, v33 offset:33284
	ds_write_b32 v6, v34 offset:33288
	ds_write_b32 v6, v35 offset:33292
	ds_write_b32 v6, v36 offset:41600
	ds_write_b32 v6, v37 offset:41604
	ds_write_b32 v6, v38 offset:41608
	ds_write_b32 v6, v39 offset:41612
	ds_write_b32 v6, v40 offset:49920
	ds_write_b32 v6, v41 offset:49924
	ds_write_b32 v6, v42 offset:49928
	ds_write_b32 v6, v43 offset:49932
	ds_write_b32 v6, v44 offset:58240
	ds_write_b32 v6, v45 offset:58244
	ds_write_b32 v6, v46 offset:58248
	ds_write_b32 v6, v47 offset:58252
	s_waitcnt lgkmcnt(0)
	s_barrier
	s_add_u32 s11, s10, 512
	s_mov_b32 s27, 0
	s_cmp_lt_u32 s11, 3392
	s_cbranch_scc0 .Lcv0_nb
	s_mov_b32 s27, 1
	s_mul_hi_u32 s15, s11, 0x13521d0
	s_mul_i32 s14, s15, 212
	s_sub_u32 s14, s11, s14
	s_lshl_b32 s18, s14, 6
	s_mov_b32 s29, 0
	s_cmp_lt_u32 s14, 88
	s_cbranch_scc1 .Lcv0_cb
	s_add_u32 s18, s18, 8
	s_cmp_lt_u32 s14, 208
	s_cbranch_scc1 .Lcv0_cb
	s_movk_i32 s18, 0x1600
	s_mov_b32 s29, 1
	s_cmp_eq_u32 s14, 208
	s_cbranch_scc1 .Lcv0_cb
	s_mov_b32 s18, 0
	s_mov_b32 s29, 2
.Lcv0_cb:
	s_mul_i32 s19, s15, 0x1a0400
	s_add_u32 s19, s19, s18
	s_lshl_b32 s19, s19, 2
	s_add_u32 s20, s4, s19
	s_addc_u32 s21, s5, 0
	s_lshl_b32 s19, s15, 9
	s_add_u32 s22, s6, s19
	s_addc_u32 s23, s7, 0
	global_load_dwordx4 v[32:35], v4, s[20:21]
	global_load_dword v48, v5, s[22:23]
	s_add_u32 s20, s20, 0x1a0400
	s_addc_u32 s21, s21, 0
	global_load_dwordx4 v[36:39], v4, s[20:21]
	global_load_dword v49, v5, s[22:23] offset:128
	s_add_u32 s20, s20, 0x1a0400
	s_addc_u32 s21, s21, 0
	global_load_dwordx4 v[40:43], v4, s[20:21]
	global_load_dword v50, v5, s[22:23] offset:256
	s_add_u32 s20, s20, 0x1a0400
	s_addc_u32 s21, s21, 0
	global_load_dwordx4 v[44:47], v4, s[20:21]
	global_load_dword v51, v5, s[22:23] offset:384
.Lcv0_nb:
	ds_read_b32 v52, v7 offset:33280
	ds_read_b32 v53, v7 offset:33540
	ds_read_b32 v54, v7 offset:33800
	ds_read_b32 v55, v7 offset:34060
	ds_read_b32 v56, v7 offset:34320
	ds_read_b32 v57, v7 offset:34580
	ds_read_b32 v58, v7 offset:34840
	ds_read_b32 v59, v7 offset:35100
	ds_read_b32 v60, v7 offset:35360
	ds_read_b32 v61, v7 offset:35620
	ds_read_b32 v62, v7 offset:35880
	ds_read_b32 v63, v7 offset:36140
	ds_read_b32 v64, v7 offset:36400
	ds_read_b32 v65, v7 offset:36660
	ds_read_b32 v66, v7 offset:36920
	ds_read_b32 v67, v7 offset:37180
	s_mul_hi_u32 s15, s10, 0x13521d0
	s_mul_i32 s14, s15, 212
	s_sub_u32 s14, s10, s14
	s_lshl_b32 s14, s14, 18
	s_lshl_b32 s15, s15, 8
	s_add_u32 s14, s14, s15
	s_add_u32 s24, s8, s14
	s_addc_u32 s25, s9, 0
	s_waitcnt lgkmcnt(14)
	v_cvt_pk_bf16_f32 v68, v52, v53
	s_waitcnt lgkmcnt(12)
	v_cvt_pk_bf16_f32 v69, v54, v55
	s_waitcnt lgkmcnt(10)
	v_cvt_pk_bf16_f32 v70, v56, v57
	s_waitcnt lgkmcnt(8)
	v_cvt_pk_bf16_f32 v71, v58, v59
	s_waitcnt lgkmcnt(6)
	v_cvt_pk_bf16_f32 v72, v60, v61
	s_waitcnt lgkmcnt(4)
	v_cvt_pk_bf16_f32 v73, v62, v63
	s_waitcnt lgkmcnt(2)
	v_cvt_pk_bf16_f32 v74, v64, v65
	s_waitcnt lgkmcnt(0)
	v_cvt_pk_bf16_f32 v75, v66, v67
	global_store_dwordx4 v8, v[68:71], s[24:25]
	global_store_dwordx4 v8, v[72:75], s[24:25] offset:16
	s_add_u32 s10, s10, 256
	s_cmp_lt_u32 s10, 3392
	s_cbranch_scc0 .Lcv0_end
	s_cmp_eq_u32 s27, 0
	s_cbranch_scc1 .Lcv0_wb
	s_waitcnt vmcnt(10)
	s_branch .Lcv0_xb

; __device__ __forceinline__ int opaque_tid(int wv) { asm volatile("" : "+s"(wv)); unsigned z = 0u; asm volatile("" : "+v"(z)); const int l = __builtin_amdgcn_mbcnt_hi(~0u, __builtin_amdgcn_mbcnt_lo(~0u, z)); return (wv << 6) | l; }
; __device__ __forceinline__ void convert_weight(int wv, const float* __restrict__ src, int ldsrc, int Ksrc, bf16_t* dst, int ldd, int koff, int ntn, const float* kscale, int mode, LAS float* tile, int pidx, int pcnt) {
;     ...
;     }
;     __syncthreads();
; __device__ __forceinline__ void init_phase(int wv, PP P) {
;     float* hp = (float*)(P->ws + WS_HP); bf16_t* hb = (bf16_t*)((unsigned char*)P->out + DO_HB); float* rsq = (float*)(P->ws + WS_RSQ); float* hsq = (float*)(P->ws + WS_HSQ);
;     const int tid = opaque_tid(wv), w = tid >> 6, lane = tid & 63;
;     for (int row = blockIdx.x * 8 + w; row < MP; row += gridDim.x * 8) {
;         const int b = row / LP, pp = row % LP;
;         const float* src = pp < PADN ? nullptr : (pp < LEADR ? P->meta + (size_t)(pp - PADN) * D : P->x + ((size_t)b * SEQ + (pp - LEADR)) * D);
;         float ss = 0.f;
; #pragma unroll
;         for (int i = 0; i < 8; ++i) {
;             const int c = (i * 64 + lane) * 4; f32x4 v = (f32x4){0.f, 0.f, 0.f, 0.f}; if (src) v = *(const f32x4*)(src + c);
.Lcv0_end:
.LBB0_61:
	s_mov_b64 s[10:11], s[0:1]
	s_barrier
	s_load_dwordx4 s[4:7], s[10:11], 0x98
	s_mov_b32 s14, s95
	s_waitcnt vmcnt(2)
	v_mov_b32_e32 v2, 0
	s_waitcnt lgkmcnt(0)
	s_add_u32 s8, s6, 0x27c84000
	v_mbcnt_lo_u32_b32 v2, -1, v2
	v_mbcnt_hi_u32_b32 v2, -1, v2
	v_lshl_or_b32 v39, s14, 6, v2
	s_addc_u32 s9, s7, 0
	v_ashrrev_i32_e32 v3, 6, v39
	s_lshl_b32 s14, s81, 3
	v_add_u32_e32 v36, s14, v3
	v_writelane_b32 v254, s14, 0
	s_movk_i32 s14, 0x4200
	v_mov_b32_e32 v35, 0
	v_cmp_gt_i32_e32 vcc, s14, v36
	s_and_saveexec_b64 s[14:15], vcc
	s_cbranch_execz .LBB0_88
	v_and_b32_e32 v3, 63, v2
	v_lshlrev_b32_e32 v2, 4, v3
	v_lshlrev_b32_e32 v4, 2, v3
	v_lshlrev_b32_e32 v3, 3, v3
	v_xor_b32_e32 v5, 4, v4
	v_xor_b32_e32 v6, 8, v4
	v_xor_b32_e32 v7, 16, v4
	v_xor_b32_e32 v8, 32, v4
	v_xor_b32_e32 v9, 64, v4
	v_xor_b32_e32 v10, 0x80, v4
	v_mov_b32_e32 v4, 0
	s_load_dwordx4 s[32:35], s[0:1], 0x0
	s_lshl_b32 s16, s81, 3
	s_add_u32 s16, s16, s95
	s_waitcnt lgkmcnt(0)
	s_add_u32 s17, s16, 0x0
	s_mul_hi_u32 s18, s17, 0x1f07c2
	s_mul_i32 s19, s18, 0x840
	s_sub_u32 s19, s17, s19
	s_mov_b32 s36, 0
	s_mov_b64 s[20:21], s[32:33]
	s_cmp_lt_u32 s19, 48
	s_cbranch_scc0 .Linit_i0_a
	s_mov_b32 s36, 1
	s_branch .Linit_i0_ld

.LBB0_116:
	s_cmp_lt_u32 s53, 0x40001
	s_mov_b64 s[44:45], 0
	s_cselect_b64 s[50:51], -1, 0
	s_and_b64 vcc, exec, s[50:51]
	s_cbranch_vccz .LBB0_109
	s_branch .LBB0_115
.LBB0_118:
	s_andn2_b64 vcc, exec, s[44:45]
	s_cbranch_vccz .LBB0_122
	s_mov_b64 s[12:13], exec
	v_mbcnt_lo_u32_b32 v16, s12, 0
	v_mbcnt_hi_u32_b32 v16, s13, v16
	v_cmp_eq_u32_e32 vcc, 0, v16
	s_and_saveexec_b64 s[10:11], vcc
	s_cbranch_execz .LBB0_121
	s_bcnt1_i32_b64 s12, s[12:13]
	v_mov_b32_e32 v16, 0
	v_mov_b32_e32 v17, s12
	global_atomic_add v16, v17, s[8:9]

; #define LAS __attribute__((address_space(3)))
; __device__ __forceinline__ PP get_params() { unsigned long long kp = (unsigned long long)__builtin_amdgcn_kernarg_segment_ptr(); asm volatile("" : "+s"(kp)); return (PP)kp; }
; __device__ __forceinline__ int opaque_tid(int wv) { asm volatile("" : "+s"(wv)); unsigned z = 0u; asm volatile("" : "+v"(z)); const int l = __builtin_amdgcn_mbcnt_hi(~0u, __builtin_amdgcn_mbcnt_lo(~0u, z)); return (wv << 6) | l; }
; __device__ __forceinline__ int opaque_bid() { int t = blockIdx.x; asm volatile("" : "+s"(t)); return t; }
; __device__ __forceinline__ void convert_weight(int wv, const float* __restrict__ src, int ldsrc, int Ksrc, bf16_t* dst, int ldd, int koff, int ntn, const float* kscale, int mode, LAS float* tile, int pidx, int pcnt) {
;     const int tid = opaque_tid(wv); const int ntk = Ksrc / 128; const int total = ntn * ntk; const int G = pcnt;
;     const int kk0 = tid >> 4, n4 = (tid & 15) * 4;
;     f32x4 v[4]; float ks[4];
;     auto prefetch = [&](int t) {
;         const int tn = t % ntn, tk = t / ntn; const int n0 = tn * 64, k0 = tk * 128;
;         int scol = n0, nvalid = 64;
;         if (mode == 1) { if (n0 < 5632) scol = n0; else if (n0 < 13312) scol = n0 + 8; else if (n0 == 13312) { scol = 5632; nvalid = 8; } else { scol = 0; nvalid = 0; } }
; #pragma unroll
;         for (int i = 0; i < 4; ++i) { const int kk = kk0 + i * 32; v[i] = (f32x4){0.f, 0.f, 0.f, 0.f};
;             if (n4 < nvalid) v[i] = *(const f32x4*)(src + (size_t)(k0 + kk) * ldsrc + scol + n4);
;             ks[i] = kscale ? kscale[k0 + kk] : 1.0f; }
;     };
;     int t = pidx; int buf = 0;
;     if (t < total) prefetch(t);
; __device__ __forceinline__ void fill_convert(int wv, LAS unsigned char* lds, int nunits, int L, int mask) {
;     const int G = (int)gridDim.x, extra = nunits % G, bid = opaque_bid();
;     if (extra != 0 && bid >= extra) convert_layer(wv, get_params(), L, mask, (LAS float*)lds, bid - extra, G - extra);
; }
.LBB0_642:
	v_readlane_b32 s4, v254, 30
	v_readlane_b32 s5, v254, 31
	s_and_b64 vcc, exec, s[4:5]
	s_cbranch_vccnz .LBB0_703
	s_mov_b32 s4, s81
	v_readlane_b32 s5, v254, 4
	s_cmp_lt_i32 s4, s5
	s_cselect_b64 s[6:7], -1, 0
	s_or_b64 s[6:7], s[82:83], s[6:7]
	s_and_b64 vcc, exec, s[6:7]
	s_cbranch_vccnz .LBB0_703
	v_readlane_b32 s5, v254, 4
	s_sub_i32 s22, s4, s5
	s_mov_b64 s[10:11], s[0:1]
	s_mov_b32 s8, s95
	v_mov_b32_e32 v0, v3
	s_cmpk_gt_i32 s22, 0xd3f
	s_cbranch_scc1 .LBB0_702
	v_mbcnt_lo_u32_b32 v10, -1, 0
	v_mbcnt_hi_u32_b32 v10, -1, v10
	v_lshl_or_b32 v10, s95, 6, v10
	v_lshrrev_b32_e32 v11, 4, v10
	v_and_b32_e32 v9, 15, v10
	v_lshlrev_b32_e32 v9, 2, v9
	v_mul_u32_u24_e32 v4, 0x3408, v11
	v_add_u32_e32 v4, v4, v9
	v_lshlrev_b32_e32 v4, 2, v4
	v_lshlrev_b32_e32 v5, 2, v11
	v_mul_u32_u24_e32 v6, 65, v11
	v_add_u32_e32 v6, v6, v9
	v_lshlrev_b32_e32 v6, 2, v6
	v_lshrrev_b32_e32 v7, 3, v10
	v_and_b32_e32 v8, 7, v10
	v_lshlrev_b32_e32 v8, 4, v8
	v_mul_u32_u24_e32 v11, 65, v8
	v_add_u32_e32 v11, v11, v7
	v_lshlrev_b32_e32 v8, 1, v8
	v_lshl_add_u32 v8, v7, 12, v8
	v_lshlrev_b32_e32 v7, 2, v11
	s_load_dwordx2 s[4:5], s[0:1], 0x18
	s_load_dwordx2 s[6:7], s[0:1], 0x10
	s_load_dwordx2 s[8:9], s[0:1], 0xa0
	s_waitcnt lgkmcnt(0)
	s_add_u32 s4, s4, 0x6810000
	s_addc_u32 s5, s5, 0
	s_add_u32 s6, s6, 0x2000
	s_addc_u32 s7, s7, 0
	s_add_u32 s8, s8, 0x23100000
	s_addc_u32 s9, s9, 0
	s_mov_b32 s10, s22
	s_mul_hi_u32 s15, s10, 0x13521d0
	s_mul_i32 s14, s15, 212
	s_sub_u32 s14, s10, s14
	s_lshl_b32 s18, s14, 6
	s_mov_b32 s28, 0
	s_cmp_lt_u32 s14, 88
	s_cbranch_scc1 .Lcv1_cp0
	s_add_u32 s18, s18, 8
	s_cmp_lt_u32 s14, 208
	s_cbranch_scc1 .Lcv1_cp0
	s_movk_i32 s18, 0x1600
	s_mov_b32 s28, 1
	s_cmp_eq_u32 s14, 208
	s_cbranch_scc1 .Lcv1_cp0
	s_mov_b32 s18, 0
	s_mov_b32 s28, 2
.Lcv1_cp0:
	s_mul_i32 s19, s15, 0x1a0400
	s_add_u32 s19, s19, s18
	s_lshl_b32 s19, s19, 2
	s_add_u32 s20, s4, s19
	s_addc_u32 s21, s5, 0
	s_lshl_b32 s19, s15, 9
	s_add_u32 s22, s6, s19
	s_addc_u32 s23, s7, 0
	global_load_dwordx4 v[12:15], v4, s[20:21]
	global_load_dword v28, v5, s[22:23]
	s_add_u32 s20, s20, 0x1a0400
	s_addc_u32 s21, s21, 0
	global_load_dwordx4 v[16:19], v4, s[20:21]
	global_load_dword v29, v5, s[22:23] offset:128
	s_add_u32 s20, s20, 0x1a0400
	s_addc_u32 s21, s21, 0
	global_load_dwordx4 v[20:23], v4, s[20:21]
	global_load_dword v30, v5, s[22:23] offset:256
	s_add_u32 s20, s20, 0x1a0400
	s_addc_u32 s21, s21, 0
	global_load_dwordx4 v[24:27], v4, s[20:21]
	global_load_dword v31, v5, s[22:23] offset:384
	s_add_u32 s11, s10, 240
	s_cmp_lt_u32 s11, 3392
	s_cbranch_scc0 .Lcv1_p1n
	s_mul_hi_u32 s15, s11, 0x13521d0
	s_mul_i32 s14, s15, 212
	s_sub_u32 s14, s11, s14
	s_lshl_b32 s18, s14, 6
	s_mov_b32 s29, 0
	s_cmp_lt_u32 s14, 88
	s_cbranch_scc1 .Lcv1_cp1
	s_add_u32 s18, s18, 8
	s_cmp_lt_u32 s14, 208
	s_cbranch_scc1 .Lcv1_cp1
	s_movk_i32 s18, 0x1600
	s_mov_b32 s29, 1
	s_cmp_eq_u32 s14, 208
	s_cbranch_scc1 .Lcv1_cp1
	s_mov_b32 s18, 0
	s_mov_b32 s29, 2

; #define LAS __attribute__((address_space(3)))
; __device__ __forceinline__ void lds_barrier() { asm volatile("s_waitcnt lgkmcnt(0)" ::: "memory"); __builtin_amdgcn_s_barrier(); asm volatile("" ::: "memory"); }
; __device__ __forceinline__ void convert_weight(int wv, const float* __restrict__ src, int ldsrc, int Ksrc, bf16_t* dst, int ldd, int koff, int ntn, const float* kscale, int mode, LAS float* tile, int pidx, int pcnt) {
;     ...
;         LAS float* tl = tile + buf * (128 * 65);
; #pragma unroll
;         for (int i = 0; i < 4; ++i) { const int kk = kk0 + i * 32;
;             tl[kk * 65 + n4 + 0] = v[i][0] * ks[i]; tl[kk * 65 + n4 + 1] = v[i][1] * ks[i]; tl[kk * 65 + n4 + 2] = v[i][2] * ks[i]; tl[kk * 65 + n4 + 3] = v[i][3] * ks[i]; }
;         lds_barrier();
;         const int tn = t % ntn, tk = t / ntn; const int n0 = tn * 64, k0 = tk * 128;
;         if (t + G < total) prefetch(t + G);
.Lcv1_ma:
	v_mul_f32_e32 v12, v12, v28
	v_mul_f32_e32 v13, v13, v28
	v_mul_f32_e32 v14, v14, v28
	v_mul_f32_e32 v15, v15, v28
	v_mul_f32_e32 v16, v16, v29
	v_mul_f32_e32 v17, v17, v29
	v_mul_f32_e32 v18, v18, v29
	v_mul_f32_e32 v19, v19, v29
	v_mul_f32_e32 v20, v20, v30
	v_mul_f32_e32 v21, v21, v30
	v_mul_f32_e32 v22, v22, v30
	v_mul_f32_e32 v23, v23, v30
	v_mul_f32_e32 v24, v24, v31
	v_mul_f32_e32 v25, v25, v31
	v_mul_f32_e32 v26, v26, v31
	v_mul_f32_e32 v27, v27, v31
	ds_write_b32 v6, v12 offset:0
	ds_write_b32 v6, v13 offset:4
	ds_write_b32 v6, v14 offset:8
	ds_write_b32 v6, v15 offset:12
	ds_write_b32 v6, v16 offset:8320
	ds_write_b32 v6, v17 offset:8324
	ds_write_b32 v6, v18 offset:8328
	ds_write_b32 v6, v19 offset:8332
	ds_write_b32 v6, v20 offset:16640
	ds_write_b32 v6, v21 offset:16644
	ds_write_b32 v6, v22 offset:16648
	ds_write_b32 v6, v23 offset:16652
	ds_write_b32 v6, v24 offset:24960
	ds_write_b32 v6, v25 offset:24964
	ds_write_b32 v6, v26 offset:24968
	ds_write_b32 v6, v27 offset:24972
	s_waitcnt lgkmcnt(0)
	s_barrier
	s_add_u32 s11, s10, 480
	s_mov_b32 s27, 0
	s_cmp_lt_u32 s11, 3392
	s_cbranch_scc0 .Lcv1_na
	s_mov_b32 s27, 1
	s_mul_hi_u32 s15, s11, 0x13521d0
	s_mul_i32 s14, s15, 212
	s_sub_u32 s14, s11, s14
	s_lshl_b32 s18, s14, 6
	s_mov_b32 s28, 0
	s_cmp_lt_u32 s14, 88
	s_cbranch_scc1 .Lcv1_ca
	s_add_u32 s18, s18, 8
	s_cmp_lt_u32 s14, 208
	s_cbranch_scc1 .Lcv1_ca
	s_movk_i32 s18, 0x1600
	s_mov_b32 s28, 1
	s_cmp_eq_u32 s14, 208
	s_cbranch_scc1 .Lcv1_ca
	s_mov_b32 s18, 0
	s_mov_b32 s28, 2

; __device__ __forceinline__ unsigned pack2(float lo, float hi) { unsigned r; asm("v_cvt_pk_bf16_f32 %0, %1, %2" : "=v"(r) : "v"(lo), "v"(hi)); return r; }
; __device__ __forceinline__ void convert_weight(int wv, const float* __restrict__ src, int ldsrc, int Ksrc, bf16_t* dst, int ldd, int koff, int ntn, const float* kscale, int mode, LAS float* tile, int pidx, int pcnt) {
;     ...
;         { const int n = tid >> 3, k16 = (tid & 7) * 16; u32x4 w0, w1;
;           w0.x = pack2(tl[(k16 + 0) * 65 + n], tl[(k16 + 1) * 65 + n]); w0.y = pack2(tl[(k16 + 2) * 65 + n], tl[(k16 + 3) * 65 + n]);
;           w0.z = pack2(tl[(k16 + 4) * 65 + n], tl[(k16 + 5) * 65 + n]); w0.w = pack2(tl[(k16 + 6) * 65 + n], tl[(k16 + 7) * 65 + n]);
;           w1.x = pack2(tl[(k16 + 8) * 65 + n], tl[(k16 + 9) * 65 + n]); w1.y = pack2(tl[(k16 + 10) * 65 + n], tl[(k16 + 11) * 65 + n]);
;           w1.z = pack2(tl[(k16 + 12) * 65 + n], tl[(k16 + 13) * 65 + n]); w1.w = pack2(tl[(k16 + 14) * 65 + n], tl[(k16 + 15) * 65 + n]);
;           bf16_t* dp = dst + (size_t)(n0 + n) * ldd + koff + k0 + k16; *(u32x4*)dp = w0; *(u32x4*)(dp + 8) = w1; }
;         buf ^= 1;
;     }
.Lcv1_na:
	ds_read_b32 v52, v7 offset:0
	ds_read_b32 v53, v7 offset:260
	ds_read_b32 v54, v7 offset:520
	ds_read_b32 v55, v7 offset:780
	ds_read_b32 v56, v7 offset:1040
	ds_read_b32 v57, v7 offset:1300
	ds_read_b32 v58, v7 offset:1560
	ds_read_b32 v59, v7 offset:1820
	ds_read_b32 v60, v7 offset:2080
	ds_read_b32 v61, v7 offset:2340
	ds_read_b32 v62, v7 offset:2600
	ds_read_b32 v63, v7 offset:2860
	ds_read_b32 v64, v7 offset:3120
	ds_read_b32 v65, v7 offset:3380
	ds_read_b32 v66, v7 offset:3640
	ds_read_b32 v67, v7 offset:3900
	s_mul_hi_u32 s15, s10, 0x13521d0
	s_mul_i32 s14, s15, 212
	s_sub_u32 s14, s10, s14
	s_lshl_b32 s14, s14, 18
	s_lshl_b32 s15, s15, 8
	s_add_u32 s14, s14, s15
	s_add_u32 s24, s8, s14
	s_addc_u32 s25, s9, 0
	s_waitcnt lgkmcnt(14)
	v_cvt_pk_bf16_f32 v68, v52, v53
	s_waitcnt lgkmcnt(12)
	v_cvt_pk_bf16_f32 v69, v54, v55
	s_waitcnt lgkmcnt(10)
	v_cvt_pk_bf16_f32 v70, v56, v57
	s_waitcnt lgkmcnt(8)
	v_cvt_pk_bf16_f32 v71, v58, v59
	s_waitcnt lgkmcnt(6)
	v_cvt_pk_bf16_f32 v72, v60, v61
	s_waitcnt lgkmcnt(4)
	v_cvt_pk_bf16_f32 v73, v62, v63
	s_waitcnt lgkmcnt(2)
	v_cvt_pk_bf16_f32 v74, v64, v65
	s_waitcnt lgkmcnt(0)
	v_cvt_pk_bf16_f32 v75, v66, v67
	global_store_dwordx4 v8, v[68:71], s[24:25]
	global_store_dwordx4 v8, v[72:75], s[24:25] offset:16
	s_add_u32 s10, s10, 240
	s_cmp_lt_u32 s10, 3392
	s_cbranch_scc0 .Lcv1_end
	s_cmp_eq_u32 s27, 0
	s_cbranch_scc1 .Lcv1_wa
	s_waitcnt vmcnt(10)
	s_branch .Lcv1_xa

; #define LAS __attribute__((address_space(3)))
; __device__ __forceinline__ void lds_barrier() { asm volatile("s_waitcnt lgkmcnt(0)" ::: "memory"); __builtin_amdgcn_s_barrier(); asm volatile("" ::: "memory"); }
; __device__ __forceinline__ void convert_weight(int wv, const float* __restrict__ src, int ldsrc, int Ksrc, bf16_t* dst, int ldd, int koff, int ntn, const float* kscale, int mode, LAS float* tile, int pidx, int pcnt) {
;     ...
;         LAS float* tl = tile + buf * (128 * 65);
; #pragma unroll
;         for (int i = 0; i < 4; ++i) { const int kk = kk0 + i * 32;
;             tl[kk * 65 + n4 + 0] = v[i][0] * ks[i]; tl[kk * 65 + n4 + 1] = v[i][1] * ks[i]; tl[kk * 65 + n4 + 2] = v[i][2] * ks[i]; tl[kk * 65 + n4 + 3] = v[i][3] * ks[i]; }
;         lds_barrier();
;         const int tn = t % ntn, tk = t / ntn; const int n0 = tn * 64, k0 = tk * 128;
;         if (t + G < total) prefetch(t + G);
.Lcv1_mb:
	v_mul_f32_e32 v32, v32, v48
	v_mul_f32_e32 v33, v33, v48
	v_mul_f32_e32 v34, v34, v48
	v_mul_f32_e32 v35, v35, v48
	v_mul_f32_e32 v36, v36, v49
	v_mul_f32_e32 v37, v37, v49
	v_mul_f32_e32 v38, v38, v49
	v_mul_f32_e32 v39, v39, v49
	v_mul_f32_e32 v40, v40, v50
	v_mul_f32_e32 v41, v41, v50
	v_mul_f32_e32 v42, v42, v50
	v_mul_f32_e32 v43, v43, v50
	v_mul_f32_e32 v44, v44, v51
	v_mul_f32_e32 v45, v45, v51
	v_mul_f32_e32 v46, v46, v51
	v_mul_f32_e32 v47, v47, v51
	ds_write_b32 v6, v32 offset:33280
	ds_write_b32 v6, v33 offset:33284
	ds_write_b32 v6, v34 offset:33288
	ds_write_b32 v6, v35 offset:33292
	ds_write_b32 v6, v36 offset:41600
	ds_write_b32 v6, v37 offset:41604
	ds_write_b32 v6, v38 offset:41608
	ds_write_b32 v6, v39 offset:41612
	ds_write_b32 v6, v40 offset:49920
	ds_write_b32 v6, v41 offset:49924
	ds_write_b32 v6, v42 offset:49928
	ds_write_b32 v6, v43 offset:49932
	ds_write_b32 v6, v44 offset:58240
	ds_write_b32 v6, v45 offset:58244
	ds_write_b32 v6, v46 offset:58248
	ds_write_b32 v6, v47 offset:58252
	s_waitcnt lgkmcnt(0)
	s_barrier
	s_add_u32 s11, s10, 480
	s_mov_b32 s27, 0
	s_cmp_lt_u32 s11, 3392
	s_cbranch_scc0 .Lcv1_nb
	s_mov_b32 s27, 1
	s_mul_hi_u32 s15, s11, 0x13521d0
	s_mul_i32 s14, s15, 212
	s_sub_u32 s14, s11, s14
	s_lshl_b32 s18, s14, 6
	s_mov_b32 s29, 0
	s_cmp_lt_u32 s14, 88
	s_cbranch_scc1 .Lcv1_cb
	s_add_u32 s18, s18, 8
	s_cmp_lt_u32 s14, 208
	s_cbranch_scc1 .Lcv1_cb
	s_movk_i32 s18, 0x1600
	s_mov_b32 s29, 1
	s_cmp_eq_u32 s14, 208
	s_cbranch_scc1 .Lcv1_cb
	s_mov_b32 s18, 0
	s_mov_b32 s29, 2

; __device__ __forceinline__ unsigned pack2(float lo, float hi) { unsigned r; asm("v_cvt_pk_bf16_f32 %0, %1, %2" : "=v"(r) : "v"(lo), "v"(hi)); return r; }
; __device__ __forceinline__ void convert_weight(int wv, const float* __restrict__ src, int ldsrc, int Ksrc, bf16_t* dst, int ldd, int koff, int ntn, const float* kscale, int mode, LAS float* tile, int pidx, int pcnt) {
;     ...
;         { const int n = tid >> 3, k16 = (tid & 7) * 16; u32x4 w0, w1;
;           w0.x = pack2(tl[(k16 + 0) * 65 + n], tl[(k16 + 1) * 65 + n]); w0.y = pack2(tl[(k16 + 2) * 65 + n], tl[(k16 + 3) * 65 + n]);
;           w0.z = pack2(tl[(k16 + 4) * 65 + n], tl[(k16 + 5) * 65 + n]); w0.w = pack2(tl[(k16 + 6) * 65 + n], tl[(k16 + 7) * 65 + n]);
;           w1.x = pack2(tl[(k16 + 8) * 65 + n], tl[(k16 + 9) * 65 + n]); w1.y = pack2(tl[(k16 + 10) * 65 + n], tl[(k16 + 11) * 65 + n]);
;           w1.z = pack2(tl[(k16 + 12) * 65 + n], tl[(k16 + 13) * 65 + n]); w1.w = pack2(tl[(k16 + 14) * 65 + n], tl[(k16 + 15) * 65 + n]);
;           bf16_t* dp = dst + (size_t)(n0 + n) * ldd + koff + k0 + k16; *(u32x4*)dp = w0; *(u32x4*)(dp + 8) = w1; }
;         buf ^= 1;
;     }
.Lcv1_nb:
	ds_read_b32 v52, v7 offset:33280
	ds_read_b32 v53, v7 offset:33540
	ds_read_b32 v54, v7 offset:33800
	ds_read_b32 v55, v7 offset:34060
	ds_read_b32 v56, v7 offset:34320
	ds_read_b32 v57, v7 offset:34580
	ds_read_b32 v58, v7 offset:34840
	ds_read_b32 v59, v7 offset:35100
	ds_read_b32 v60, v7 offset:35360
	ds_read_b32 v61, v7 offset:35620
	ds_read_b32 v62, v7 offset:35880
	ds_read_b32 v63, v7 offset:36140
	ds_read_b32 v64, v7 offset:36400
	ds_read_b32 v65, v7 offset:36660
	ds_read_b32 v66, v7 offset:36920
	ds_read_b32 v67, v7 offset:37180
	s_mul_hi_u32 s15, s10, 0x13521d0
	s_mul_i32 s14, s15, 212
	s_sub_u32 s14, s10, s14
	s_lshl_b32 s14, s14, 18
	s_lshl_b32 s15, s15, 8
	s_add_u32 s14, s14, s15
	s_add_u32 s24, s8, s14
	s_addc_u32 s25, s9, 0
	s_waitcnt lgkmcnt(14)
	v_cvt_pk_bf16_f32 v68, v52, v53
	s_waitcnt lgkmcnt(12)
	v_cvt_pk_bf16_f32 v69, v54, v55
	s_waitcnt lgkmcnt(10)
	v_cvt_pk_bf16_f32 v70, v56, v57
	s_waitcnt lgkmcnt(8)
	v_cvt_pk_bf16_f32 v71, v58, v59
	s_waitcnt lgkmcnt(6)
	v_cvt_pk_bf16_f32 v72, v60, v61
	s_waitcnt lgkmcnt(4)
	v_cvt_pk_bf16_f32 v73, v62, v63
	s_waitcnt lgkmcnt(2)
	v_cvt_pk_bf16_f32 v74, v64, v65
	s_waitcnt lgkmcnt(0)
	v_cvt_pk_bf16_f32 v75, v66, v67
	global_store_dwordx4 v8, v[68:71], s[24:25]
	global_store_dwordx4 v8, v[72:75], s[24:25] offset:16
	s_add_u32 s10, s10, 240
	s_cmp_lt_u32 s10, 3392
	s_cbranch_scc0 .Lcv1_end
	s_cmp_eq_u32 s27, 0
	s_cbranch_scc1 .Lcv1_wb
	s_waitcnt vmcnt(10)
	s_branch .Lcv1_xb

; __device__ __forceinline__ void convert_weight(int wv, const float* __restrict__ src, int ldsrc, int Ksrc, bf16_t* dst, int ldd, int koff, int ntn, const float* kscale, int mode, LAS float* tile, int pidx, int pcnt) {
;     ...
;     }
;     __syncthreads();
.Lcv1_end:
.LBB0_702:
	s_waitcnt lgkmcnt(0)
	s_barrier

; #define LAS __attribute__((address_space(3)))
; __device__ __forceinline__ PP get_params() { unsigned long long kp = (unsigned long long)__builtin_amdgcn_kernarg_segment_ptr(); asm volatile("" : "+s"(kp)); return (PP)kp; }
; __device__ __forceinline__ int opaque_tid(int wv) { asm volatile("" : "+s"(wv)); unsigned z = 0u; asm volatile("" : "+v"(z)); const int l = __builtin_amdgcn_mbcnt_hi(~0u, __builtin_amdgcn_mbcnt_lo(~0u, z)); return (wv << 6) | l; }
; __device__ __forceinline__ int opaque_bid() { int t = blockIdx.x; asm volatile("" : "+s"(t)); return t; }
; __device__ __forceinline__ void convert_weight(int wv, const float* __restrict__ src, int ldsrc, int Ksrc, bf16_t* dst, int ldd, int koff, int ntn, const float* kscale, int mode, LAS float* tile, int pidx, int pcnt) {
;     const int tid = opaque_tid(wv); const int ntk = Ksrc / 128; const int total = ntn * ntk; const int G = pcnt;
;     const int kk0 = tid >> 4, n4 = (tid & 15) * 4;
;     f32x4 v[4]; float ks[4];
;     auto prefetch = [&](int t) {
;         const int tn = t % ntn, tk = t / ntn; const int n0 = tn * 64, k0 = tk * 128;
;         int scol = n0, nvalid = 64;
;         if (mode == 1) { if (n0 < 5632) scol = n0; else if (n0 < 13312) scol = n0 + 8; else if (n0 == 13312) { scol = 5632; nvalid = 8; } else { scol = 0; nvalid = 0; } }
; #pragma unroll
;         for (int i = 0; i < 4; ++i) { const int kk = kk0 + i * 32; v[i] = (f32x4){0.f, 0.f, 0.f, 0.f};
;             if (n4 < nvalid) v[i] = *(const f32x4*)(src + (size_t)(k0 + kk) * ldsrc + scol + n4);
;             ks[i] = kscale ? kscale[k0 + kk] : 1.0f; }
;     };
;     int t = pidx; int buf = 0;
;     if (t < total) prefetch(t);
; __device__ __forceinline__ void fill_convert(int wv, LAS unsigned char* lds, int nunits, int L, int mask) {
;     const int G = (int)gridDim.x, extra = nunits % G, bid = opaque_bid();
;     if (extra != 0 && bid >= extra) convert_layer(wv, get_params(), L, mask, (LAS float*)lds, bid - extra, G - extra);
; }
.LBB0_945:
	v_readlane_b32 s4, v254, 30
	v_readlane_b32 s5, v254, 31
	s_and_b64 vcc, exec, s[4:5]
	s_cbranch_vccnz .LBB0_970
	s_mov_b32 s4, s81
	s_movk_i32 s5, 64
	s_cmp_lt_i32 s4, s5
	s_cselect_b64 s[6:7], -1, 0
	s_or_b64 s[6:7], s[82:83], s[6:7]
	s_and_b64 vcc, exec, s[6:7]
	s_cbranch_vccnz .LBB0_970
	s_movk_i32 s5, 64
	s_sub_i32 s16, s4, s5
	s_mov_b64 s[10:11], s[0:1]
	s_mov_b32 s4, s95
	v_mov_b32_e32 v0, v3
	s_cmpk_gt_i32 s16, 0xaff
	s_cbranch_scc1 .LBB0_969
	v_mbcnt_lo_u32_b32 v10, -1, 0
	v_mbcnt_hi_u32_b32 v10, -1, v10
	v_lshl_or_b32 v10, s95, 6, v10
	v_lshrrev_b32_e32 v11, 4, v10
	v_and_b32_e32 v9, 15, v10
	v_lshlrev_b32_e32 v9, 2, v9
	v_mul_u32_u24_e32 v4, 0x2c00, v11
	v_add_u32_e32 v4, v4, v9
	v_lshlrev_b32_e32 v4, 2, v4
	v_lshlrev_b32_e32 v5, 2, v11
	v_mul_u32_u24_e32 v6, 65, v11
	v_add_u32_e32 v6, v6, v9
	v_lshlrev_b32_e32 v6, 2, v6
	v_lshrrev_b32_e32 v7, 3, v10
	v_and_b32_e32 v8, 7, v10
	v_lshlrev_b32_e32 v8, 4, v8
	v_mul_u32_u24_e32 v11, 65, v8
	v_add_u32_e32 v11, v11, v7
	v_lshlrev_b32_e32 v8, 1, v8
	v_lshl_add_u32 v8, v7, 12, v8
	v_lshlrev_b32_e32 v7, 2, v11
	s_load_dwordx2 s[4:5], s[0:1], 0x70
	s_load_dwordx2 s[6:7], s[0:1], 0x68
	s_load_dwordx2 s[8:9], s[0:1], 0x98
	s_waitcnt lgkmcnt(0)
	s_add_u32 s4, s4, 0x5800000
	s_addc_u32 s5, s5, 0
	s_add_u32 s6, s6, 0x2000
	s_addc_u32 s7, s7, 0
	s_add_u32 s8, s8, 0x5200000
	s_addc_u32 s9, s9, 0
	s_mov_b32 s10, s16
	s_mul_hi_u32 s15, s10, 0x1745d18
	s_mul_i32 s14, s15, 176
	s_sub_u32 s14, s10, s14
	s_lshl_b32 s18, s14, 6
	s_mov_b32 s28, 0
	s_mul_i32 s19, s15, 0x160000
	s_add_u32 s19, s19, s18
	s_lshl_b32 s19, s19, 2
	s_add_u32 s20, s4, s19
	s_addc_u32 s21, s5, 0
	s_lshl_b32 s19, s15, 9
	s_add_u32 s22, s6, s19
	s_addc_u32 s23, s7, 0
	global_load_dwordx4 v[12:15], v4, s[20:21]
	global_load_dword v28, v5, s[22:23]
	s_add_u32 s20, s20, 0x160000
	s_addc_u32 s21, s21, 0
	global_load_dwordx4 v[16:19], v4, s[20:21]
	global_load_dword v29, v5, s[22:23] offset:128
	s_add_u32 s20, s20, 0x160000
	s_addc_u32 s21, s21, 0
	global_load_dwordx4 v[20:23], v4, s[20:21]
	global_load_dword v30, v5, s[22:23] offset:256
	s_add_u32 s20, s20, 0x160000
	s_addc_u32 s21, s21, 0
	global_load_dwordx4 v[24:27], v4, s[20:21]
	global_load_dword v31, v5, s[22:23] offset:384
	s_add_u32 s11, s10, 192
	s_cmp_lt_u32 s11, 2816
	s_cbranch_scc0 .Lcv2_p1n
	s_mul_hi_u32 s15, s11, 0x1745d18
	s_mul_i32 s14, s15, 176
	s_sub_u32 s14, s11, s14
	s_lshl_b32 s18, s14, 6
	s_mov_b32 s29, 0
	s_mul_i32 s19, s15, 0x160000
	s_add_u32 s19, s19, s18
	s_lshl_b32 s19, s19, 2
	s_add_u32 s20, s4, s19
	s_addc_u32 s21, s5, 0
	s_lshl_b32 s19, s15, 9
	s_add_u32 s22, s6, s19
	s_addc_u32 s23, s7, 0
	global_load_dwordx4 v[32:35], v4, s[20:21]
	global_load_dword v48, v5, s[22:23]
	s_add_u32 s20, s20, 0x160000
	s_addc_u32 s21, s21, 0
	global_load_dwordx4 v[36:39], v4, s[20:21]
	global_load_dword v49, v5, s[22:23] offset:128
	s_add_u32 s20, s20, 0x160000
	s_addc_u32 s21, s21, 0
	global_load_dwordx4 v[40:43], v4, s[20:21]
	global_load_dword v50, v5, s[22:23] offset:256
	s_add_u32 s20, s20, 0x160000
	s_addc_u32 s21, s21, 0
	global_load_dwordx4 v[44:47], v4, s[20:21]
	global_load_dword v51, v5, s[22:23] offset:384
	s_waitcnt vmcnt(8)
	s_branch .Lcv2_loop

; #define LAS __attribute__((address_space(3)))
; __device__ __forceinline__ void lds_barrier() { asm volatile("s_waitcnt lgkmcnt(0)" ::: "memory"); __builtin_amdgcn_s_barrier(); asm volatile("" ::: "memory"); }
; __device__ __forceinline__ unsigned pack2(float lo, float hi) { unsigned r; asm("v_cvt_pk_bf16_f32 %0, %1, %2" : "=v"(r) : "v"(lo), "v"(hi)); return r; }
; __device__ __forceinline__ void convert_weight(int wv, const float* __restrict__ src, int ldsrc, int Ksrc, bf16_t* dst, int ldd, int koff, int ntn, const float* kscale, int mode, LAS float* tile, int pidx, int pcnt) {
;     ...
;     for (; t < total; t += G) {
;         LAS float* tl = tile + buf * (128 * 65);
; #pragma unroll
;         for (int i = 0; i < 4; ++i) { const int kk = kk0 + i * 32;
;             tl[kk * 65 + n4 + 0] = v[i][0] * ks[i]; tl[kk * 65 + n4 + 1] = v[i][1] * ks[i]; tl[kk * 65 + n4 + 2] = v[i][2] * ks[i]; tl[kk * 65 + n4 + 3] = v[i][3] * ks[i]; }
;         lds_barrier();
;         const int tn = t % ntn, tk = t / ntn; const int n0 = tn * 64, k0 = tk * 128;
;         if (t + G < total) prefetch(t + G);
;         { const int n = tid >> 3, k16 = (tid & 7) * 16; u32x4 w0, w1;
;           w0.x = pack2(tl[(k16 + 0) * 65 + n], tl[(k16 + 1) * 65 + n]); w0.y = pack2(tl[(k16 + 2) * 65 + n], tl[(k16 + 3) * 65 + n]);
;           w0.z = pack2(tl[(k16 + 4) * 65 + n], tl[(k16 + 5) * 65 + n]); w0.w = pack2(tl[(k16 + 6) * 65 + n], tl[(k16 + 7) * 65 + n]);
;           w1.x = pack2(tl[(k16 + 8) * 65 + n], tl[(k16 + 9) * 65 + n]); w1.y = pack2(tl[(k16 + 10) * 65 + n], tl[(k16 + 11) * 65 + n]);
;           w1.z = pack2(tl[(k16 + 12) * 65 + n], tl[(k16 + 13) * 65 + n]); w1.w = pack2(tl[(k16 + 14) * 65 + n], tl[(k16 + 15) * 65 + n]);
;           bf16_t* dp = dst + (size_t)(n0 + n) * ldd + koff + k0 + k16; *(u32x4*)dp = w0; *(u32x4*)(dp + 8) = w1; }
;         buf ^= 1;
;     }
.Lcv2_loop:
	v_mul_f32_e32 v12, v12, v28
	v_mul_f32_e32 v13, v13, v28
	v_mul_f32_e32 v14, v14, v28
	v_mul_f32_e32 v15, v15, v28
	v_mul_f32_e32 v16, v16, v29
	v_mul_f32_e32 v17, v17, v29
	v_mul_f32_e32 v18, v18, v29
	v_mul_f32_e32 v19, v19, v29
	v_mul_f32_e32 v20, v20, v30
	v_mul_f32_e32 v21, v21, v30
	v_mul_f32_e32 v22, v22, v30
	v_mul_f32_e32 v23, v23, v30
	v_mul_f32_e32 v24, v24, v31
	v_mul_f32_e32 v25, v25, v31
	v_mul_f32_e32 v26, v26, v31
	v_mul_f32_e32 v27, v27, v31
	ds_write_b32 v6, v12 offset:0
	ds_write_b32 v6, v13 offset:4
	ds_write_b32 v6, v14 offset:8
	ds_write_b32 v6, v15 offset:12
	ds_write_b32 v6, v16 offset:8320
	ds_write_b32 v6, v17 offset:8324
	ds_write_b32 v6, v18 offset:8328
	ds_write_b32 v6, v19 offset:8332
	ds_write_b32 v6, v20 offset:16640
	ds_write_b32 v6, v21 offset:16644
	ds_write_b32 v6, v22 offset:16648
	ds_write_b32 v6, v23 offset:16652
	ds_write_b32 v6, v24 offset:24960
	ds_write_b32 v6, v25 offset:24964
	ds_write_b32 v6, v26 offset:24968
	ds_write_b32 v6, v27 offset:24972
	s_waitcnt lgkmcnt(0)
	s_barrier
	s_add_u32 s11, s10, 384
	s_mov_b32 s27, 0
	s_cmp_lt_u32 s11, 2816
	s_cbranch_scc0 .Lcv2_na
	s_mov_b32 s27, 1
	s_mul_hi_u32 s15, s11, 0x1745d18
	s_mul_i32 s14, s15, 176
	s_sub_u32 s14, s11, s14
	s_lshl_b32 s18, s14, 6
	s_mov_b32 s28, 0
	s_mul_i32 s19, s15, 0x160000
	s_add_u32 s19, s19, s18
	s_lshl_b32 s19, s19, 2
	s_add_u32 s20, s4, s19
	s_addc_u32 s21, s5, 0
	s_lshl_b32 s19, s15, 9
	s_add_u32 s22, s6, s19
	s_addc_u32 s23, s7, 0
	global_load_dwordx4 v[12:15], v4, s[20:21]
	global_load_dword v28, v5, s[22:23]
	s_add_u32 s20, s20, 0x160000
	s_addc_u32 s21, s21, 0
	global_load_dwordx4 v[16:19], v4, s[20:21]
	global_load_dword v29, v5, s[22:23] offset:128
	s_add_u32 s20, s20, 0x160000
	s_addc_u32 s21, s21, 0
	global_load_dwordx4 v[20:23], v4, s[20:21]
	global_load_dword v30, v5, s[22:23] offset:256
	s_add_u32 s20, s20, 0x160000
	s_addc_u32 s21, s21, 0
	global_load_dwordx4 v[24:27], v4, s[20:21]
	global_load_dword v31, v5, s[22:23] offset:384
.Lcv2_na:
	ds_read_b32 v52, v7 offset:0
	ds_read_b32 v53, v7 offset:260
	ds_read_b32 v54, v7 offset:520
	ds_read_b32 v55, v7 offset:780
	ds_read_b32 v56, v7 offset:1040
	ds_read_b32 v57, v7 offset:1300
	ds_read_b32 v58, v7 offset:1560
	ds_read_b32 v59, v7 offset:1820
	ds_read_b32 v60, v7 offset:2080
	ds_read_b32 v61, v7 offset:2340
	ds_read_b32 v62, v7 offset:2600
	ds_read_b32 v63, v7 offset:2860
	ds_read_b32 v64, v7 offset:3120
	ds_read_b32 v65, v7 offset:3380
	ds_read_b32 v66, v7 offset:3640
	ds_read_b32 v67, v7 offset:3900
	s_mul_hi_u32 s15, s10, 0x1745d18
	s_mul_i32 s14, s15, 176
	s_sub_u32 s14, s10, s14
	s_lshl_b32 s14, s14, 18
	s_lshl_b32 s15, s15, 8
	s_add_u32 s14, s14, s15
	s_add_u32 s24, s8, s14
	s_addc_u32 s25, s9, 0
	s_waitcnt lgkmcnt(14)
	v_cvt_pk_bf16_f32 v68, v52, v53
	s_waitcnt lgkmcnt(12)
	v_cvt_pk_bf16_f32 v69, v54, v55
	s_waitcnt lgkmcnt(10)
	v_cvt_pk_bf16_f32 v70, v56, v57
	s_waitcnt lgkmcnt(8)
	v_cvt_pk_bf16_f32 v71, v58, v59
	s_waitcnt lgkmcnt(6)
	v_cvt_pk_bf16_f32 v72, v60, v61
	s_waitcnt lgkmcnt(4)
	v_cvt_pk_bf16_f32 v73, v62, v63
	s_waitcnt lgkmcnt(2)
	v_cvt_pk_bf16_f32 v74, v64, v65
	s_waitcnt lgkmcnt(0)
	v_cvt_pk_bf16_f32 v75, v66, v67
	global_store_dwordx4 v8, v[68:71], s[24:25]
	global_store_dwordx4 v8, v[72:75], s[24:25] offset:16
	s_add_u32 s10, s10, 192
	s_cmp_lt_u32 s10, 2816
	s_cbranch_scc0 .Lcv2_end
	s_cmp_eq_u32 s27, 0
	s_cbranch_scc1 .Lcv2_wa
	s_waitcnt vmcnt(10)
	s_branch .Lcv2_xa

; #define LAS __attribute__((address_space(3)))
; __device__ __forceinline__ void lds_barrier() { asm volatile("s_waitcnt lgkmcnt(0)" ::: "memory"); __builtin_amdgcn_s_barrier(); asm volatile("" ::: "memory"); }
; __device__ __forceinline__ unsigned pack2(float lo, float hi) { unsigned r; asm("v_cvt_pk_bf16_f32 %0, %1, %2" : "=v"(r) : "v"(lo), "v"(hi)); return r; }
; __device__ __forceinline__ void convert_weight(int wv, const float* __restrict__ src, int ldsrc, int Ksrc, bf16_t* dst, int ldd, int koff, int ntn, const float* kscale, int mode, LAS float* tile, int pidx, int pcnt) {
;     ...
;     for (; t < total; t += G) {
;         LAS float* tl = tile + buf * (128 * 65);
; #pragma unroll
;         for (int i = 0; i < 4; ++i) { const int kk = kk0 + i * 32;
;             tl[kk * 65 + n4 + 0] = v[i][0] * ks[i]; tl[kk * 65 + n4 + 1] = v[i][1] * ks[i]; tl[kk * 65 + n4 + 2] = v[i][2] * ks[i]; tl[kk * 65 + n4 + 3] = v[i][3] * ks[i]; }
;         lds_barrier();
;         const int tn = t % ntn, tk = t / ntn; const int n0 = tn * 64, k0 = tk * 128;
;         if (t + G < total) prefetch(t + G);
;         { const int n = tid >> 3, k16 = (tid & 7) * 16; u32x4 w0, w1;
;           w0.x = pack2(tl[(k16 + 0) * 65 + n], tl[(k16 + 1) * 65 + n]); w0.y = pack2(tl[(k16 + 2) * 65 + n], tl[(k16 + 3) * 65 + n]);
;           w0.z = pack2(tl[(k16 + 4) * 65 + n], tl[(k16 + 5) * 65 + n]); w0.w = pack2(tl[(k16 + 6) * 65 + n], tl[(k16 + 7) * 65 + n]);
;           w1.x = pack2(tl[(k16 + 8) * 65 + n], tl[(k16 + 9) * 65 + n]); w1.y = pack2(tl[(k16 + 10) * 65 + n], tl[(k16 + 11) * 65 + n]);
;           w1.z = pack2(tl[(k16 + 12) * 65 + n], tl[(k16 + 13) * 65 + n]); w1.w = pack2(tl[(k16 + 14) * 65 + n], tl[(k16 + 15) * 65 + n]);
;           bf16_t* dp = dst + (size_t)(n0 + n) * ldd + koff + k0 + k16; *(u32x4*)dp = w0; *(u32x4*)(dp + 8) = w1; }
;         buf ^= 1;
;     }
.Lcv2_xa:
	v_mul_f32_e32 v32, v32, v48
	v_mul_f32_e32 v33, v33, v48
	v_mul_f32_e32 v34, v34, v48
	v_mul_f32_e32 v35, v35, v48
	v_mul_f32_e32 v36, v36, v49
	v_mul_f32_e32 v37, v37, v49
	v_mul_f32_e32 v38, v38, v49
	v_mul_f32_e32 v39, v39, v49
	v_mul_f32_e32 v40, v40, v50
	v_mul_f32_e32 v41, v41, v50
	v_mul_f32_e32 v42, v42, v50
	v_mul_f32_e32 v43, v43, v50
	v_mul_f32_e32 v44, v44, v51
	v_mul_f32_e32 v45, v45, v51
	v_mul_f32_e32 v46, v46, v51
	v_mul_f32_e32 v47, v47, v51
	ds_write_b32 v6, v32 offset:33280
	ds_write_b32 v6, v33 offset:33284
	ds_write_b32 v6, v34 offset:33288
	ds_write_b32 v6, v35 offset:33292
	ds_write_b32 v6, v36 offset:41600
	ds_write_b32 v6, v37 offset:41604
	ds_write_b32 v6, v38 offset:41608
	ds_write_b32 v6, v39 offset:41612
	ds_write_b32 v6, v40 offset:49920
	ds_write_b32 v6, v41 offset:49924
	ds_write_b32 v6, v42 offset:49928
	ds_write_b32 v6, v43 offset:49932
	ds_write_b32 v6, v44 offset:58240
	ds_write_b32 v6, v45 offset:58244
	ds_write_b32 v6, v46 offset:58248
	ds_write_b32 v6, v47 offset:58252
	s_waitcnt lgkmcnt(0)
	s_barrier
	s_add_u32 s11, s10, 384
	s_mov_b32 s27, 0
	s_cmp_lt_u32 s11, 2816
	s_cbranch_scc0 .Lcv2_nb
	s_mov_b32 s27, 1
	s_mul_hi_u32 s15, s11, 0x1745d18
	s_mul_i32 s14, s15, 176
	s_sub_u32 s14, s11, s14
	s_lshl_b32 s18, s14, 6
	s_mov_b32 s29, 0
	s_mul_i32 s19, s15, 0x160000
	s_add_u32 s19, s19, s18
	s_lshl_b32 s19, s19, 2
	s_add_u32 s20, s4, s19
	s_addc_u32 s21, s5, 0
	s_lshl_b32 s19, s15, 9
	s_add_u32 s22, s6, s19
	s_addc_u32 s23, s7, 0
	global_load_dwordx4 v[32:35], v4, s[20:21]
	global_load_dword v48, v5, s[22:23]
	s_add_u32 s20, s20, 0x160000
	s_addc_u32 s21, s21, 0
	global_load_dwordx4 v[36:39], v4, s[20:21]
	global_load_dword v49, v5, s[22:23] offset:128
	s_add_u32 s20, s20, 0x160000
	s_addc_u32 s21, s21, 0
	global_load_dwordx4 v[40:43], v4, s[20:21]
	global_load_dword v50, v5, s[22:23] offset:256
	s_add_u32 s20, s20, 0x160000
	s_addc_u32 s21, s21, 0
	global_load_dwordx4 v[44:47], v4, s[20:21]
	global_load_dword v51, v5, s[22:23] offset:384
.Lcv2_nb:
	ds_read_b32 v52, v7 offset:33280
	ds_read_b32 v53, v7 offset:33540
	ds_read_b32 v54, v7 offset:33800
	ds_read_b32 v55, v7 offset:34060
	ds_read_b32 v56, v7 offset:34320
	ds_read_b32 v57, v7 offset:34580
	ds_read_b32 v58, v7 offset:34840
	ds_read_b32 v59, v7 offset:35100
	ds_read_b32 v60, v7 offset:35360
	ds_read_b32 v61, v7 offset:35620
	ds_read_b32 v62, v7 offset:35880
	ds_read_b32 v63, v7 offset:36140
	ds_read_b32 v64, v7 offset:36400
	ds_read_b32 v65, v7 offset:36660
	ds_read_b32 v66, v7 offset:36920
	ds_read_b32 v67, v7 offset:37180
	s_mul_hi_u32 s15, s10, 0x1745d18
	s_mul_i32 s14, s15, 176
	s_sub_u32 s14, s10, s14
	s_lshl_b32 s14, s14, 18
	s_lshl_b32 s15, s15, 8
	s_add_u32 s14, s14, s15
	s_add_u32 s24, s8, s14
	s_addc_u32 s25, s9, 0
	s_waitcnt lgkmcnt(14)
	v_cvt_pk_bf16_f32 v68, v52, v53
	s_waitcnt lgkmcnt(12)
	v_cvt_pk_bf16_f32 v69, v54, v55
	s_waitcnt lgkmcnt(10)
	v_cvt_pk_bf16_f32 v70, v56, v57
	s_waitcnt lgkmcnt(8)
	v_cvt_pk_bf16_f32 v71, v58, v59
	s_waitcnt lgkmcnt(6)
	v_cvt_pk_bf16_f32 v72, v60, v61
	s_waitcnt lgkmcnt(4)
	v_cvt_pk_bf16_f32 v73, v62, v63
	s_waitcnt lgkmcnt(2)
	v_cvt_pk_bf16_f32 v74, v64, v65
	s_waitcnt lgkmcnt(0)
	v_cvt_pk_bf16_f32 v75, v66, v67
	global_store_dwordx4 v8, v[68:71], s[24:25]
	global_store_dwordx4 v8, v[72:75], s[24:25] offset:16
	s_add_u32 s10, s10, 192
	s_cmp_lt_u32 s10, 2816
	s_cbranch_scc0 .Lcv2_end
	s_cmp_eq_u32 s27, 0
	s_cbranch_scc1 .Lcv2_wb
	s_waitcnt vmcnt(10)
	s_branch .Lcv2_xb
